# norm2 phase (context rows): residual-row pieces and split-K slab fold loads issued together (one wait each) instead of ~13 serial round trips
# speedup vs baseline: 1.0100x; 1.0031x over previous
; __device__ __forceinline__ f32x4 unpack4(const v2u w) { f32x4 r; r[0] = bflo(w.x); r[1] = bfhi(w.x); r[2] = bflo(w.y); r[3] = bfhi(w.y); return r; }
; __device__ __forceinline__ int fresh_lane() { int t; asm volatile("v_mbcnt_lo_u32_b32 %0, -1, 0\n\tv_mbcnt_hi_u32_b32 %0, -1, %0" : "=v"(t)); return t; }
; __device__ __forceinline__ void phase_norm(const Frame& F, int l, int which, int row_lo, int nrows, int nslab, const float* sgate) {
;     const float* nwp = (which == 0 ? F.norm1_w : F.norm2_w) + l * 1024;
;     const bool init = (which == 0 && l == 0);
;     const int lane = fresh_lane();
;     f32x4 nwv[4];
; #pragma unroll
;     for (int j = 0; j < 4; ++j) nwv[j] = *(const f32x4*)(nwp + 256 * j + 4 * lane);
;     int m = row_lo + F.gw; if (m >= nrows) return;
;     f32x4 v[4], vn[4];
;     if (init) { const bool lat = m < MLAT; const float* src = lat ? F.x + (size_t)m * 1024 : F.ctx + (size_t)(m - MLAT) * 1024;
; #pragma unroll
;       for (int j = 0; j < 4; ++j) v[j] = *(const f32x4*)(src + 256 * j + 4 * lane); }
;     else {
; #pragma unroll
;       for (int j = 0; j < 4; ++j) v[j] = unpack4(*(const v2u*)(F.XB + (size_t)m * 1024 + 256 * j + 4 * lane)); }
.LBB0_62:
	v_readlane_b32 s4, v254, 56
	s_and_b64 vcc, exec, s[10:11]
	v_readlane_b32 s5, v254, 57
	s_cbranch_vccz .LBB0_78
	v_readlane_b32 s0, v251, 10
	s_cmp_ge_i32 s0, s3
	v_readlane_b32 s1, v251, 11
	v_mbcnt_lo_u32_b32 v0, -1, 0
	v_mbcnt_hi_u32_b32 v0, -1, v0
	s_cbranch_scc1 .LBB0_78
	s_load_dwordx2 s[0:1], s[4:5], 0x38
	v_readlane_b32 s4, v254, 44
	v_readlane_b32 s5, v254, 45
	s_lshl_b64 s[4:5], s[4:5], 2
	s_waitcnt vmcnt(0)
	v_lshlrev_b32_e32 v50, 2, v0
	s_waitcnt lgkmcnt(0)
	s_add_u32 s0, s0, s4
	v_ashrrev_i32_e32 v51, 31, v50
	s_addc_u32 s1, s1, s5
	v_lshlrev_b64 v[18:19], 2, v[50:51]
	v_lshl_add_u64 v[14:15], s[0:1], 0, v[18:19]
	v_readlane_b32 s0, v254, 37
	s_mul_i32 s0, s0, 9
	s_add_i32 s0, s0, 8
	s_mul_hi_i32 s1, s0, 0x6000
	s_mulk_i32 s0, 0x6000
	s_add_u32 s0, s60, s0
	s_addc_u32 s1, s61, s1
	v_readlane_b32 s4, v253, 17
	v_readlane_b32 s6, v254, 39
	v_readlane_b32 s5, v253, 18
	s_add_u32 s4, s6, s4
	v_readlane_b32 s6, v254, 40
	s_addc_u32 s5, s6, s5
	v_lshlrev_b64 v[20:21], 1, v[50:51]
	v_lshl_add_u64 v[22:23], s[4:5], 0, v[20:21]
	global_load_dwordx4 v[2:5], v[14:15], off
	global_load_dwordx4 v[6:9], v[14:15], off offset:1024
	global_load_dwordx4 v[10:13], v[14:15], off offset:2048
	s_nop 0
	global_load_dwordx4 v[14:17], v[14:15], off offset:3072
	v_lshl_add_u64 v[18:19], s[0:1], 0, v[18:19]
	global_load_dwordx2 v[24:25], v[22:23], off
	global_load_dwordx2 v[142:143], v[22:23], off offset:512
	global_load_dwordx2 v[144:145], v[22:23], off offset:1024
	global_load_dwordx2 v[146:147], v[22:23], off offset:1536
	s_mov_b64 s[0:1], 0x2000
	v_lshl_add_u64 v[52:53], v[18:19], 0, s[0:1]
	v_readlane_b32 s0, v254, 41
	v_and_b32_e32 v18, 64, v232
	v_readlane_b32 s1, v254, 42
	v_xor_b32_e32 v0, 16, v232
	v_add_u32_e32 v18, 64, v18
	v_lshl_add_u64 v[60:61], s[0:1], 0, v[20:21]
	v_readlane_b32 s0, v253, 19
	v_cmp_lt_i32_e32 vcc, v0, v18
	v_xor_b32_e32 v19, 32, v232
	v_readlane_b32 s1, v253, 20
	v_cndmask_b32_e32 v0, v232, v0, vcc
	v_cmp_lt_i32_e32 vcc, v19, v18
	v_lshl_add_u64 v[64:65], s[0:1], 0, v[20:21]
	v_readlane_b32 s0, v253, 21
	v_cndmask_b32_e32 v18, v232, v19, vcc
	v_readlane_b32 s1, v253, 22
	v_lshlrev_b32_e32 v0, 2, v0
	v_lshlrev_b32_e32 v80, 2, v18
	v_lshl_add_u64 v[66:67], s[0:1], 0, v[20:21]
	v_mov_b32_e32 v81, 0
	s_mov_b32 s92, s94
	v_mov_b32_e32 v82, 0
	v_mov_b32_e32 v83, 0
	v_mov_b32_e32 v84, 0
	v_mov_b32_e32 v85, 0
	v_mov_b32_e32 v86, 0
	v_mov_b32_e32 v87, 0
	v_mov_b32_e32 v88, 0
	v_mov_b32_e32 v89, 0
	v_mov_b32_e32 v90, 0
	v_mov_b32_e32 v91, 0
	v_mov_b32_e32 v92, 0
	v_mov_b32_e32 v93, 0
	v_mov_b32_e32 v94, 0
	v_mov_b32_e32 v95, 0
	v_mov_b32_e32 v96, 0
	s_waitcnt vmcnt(0)
	v_lshlrev_b32_e32 v72, 16, v24
	v_and_b32_e32 v73, 0xffff0000, v24
	v_lshlrev_b32_e32 v74, 16, v25
	v_and_b32_e32 v75, 0xffff0000, v25
	v_lshlrev_b32_e32 v68, 16, v142
	v_and_b32_e32 v69, 0xffff0000, v142
	v_lshlrev_b32_e32 v70, 16, v143
	v_and_b32_e32 v71, 0xffff0000, v143
	v_lshlrev_b32_e32 v58, 16, v144
	v_and_b32_e32 v59, 0xffff0000, v144
	v_lshlrev_b32_e32 v62, 16, v145
	v_and_b32_e32 v63, 0xffff0000, v145
	v_lshlrev_b32_e32 v54, 16, v146
	v_and_b32_e32 v55, 0xffff0000, v146
	v_lshlrev_b32_e32 v56, 16, v147
	v_and_b32_e32 v57, 0xffff0000, v147
	s_branch .LBB0_66

; __device__ __forceinline__ f32x4 unpack4(const v2u w) { f32x4 r; r[0] = bflo(w.x); r[1] = bfhi(w.x); r[2] = bflo(w.y); r[3] = bfhi(w.y); return r; }
; __device__ __forceinline__ void phase_norm(const Frame& F, int l, int which, int row_lo, int nrows, int nslab, const float* sgate) {
;     ...
;         const bool red = !lat && nslab > 0;
;         if (red) {
; #pragma unroll
;             for (int j = 0; j < 4; ++j) { f32x4 a = {0.f, 0.f, 0.f, 0.f};
;                 for (int k = 0; k < nslab; ++k) a += unpack4(*(const v2u*)((const bf16_t*)F.SLAB + ((size_t)k * MCTX + (m - MLAT)) * 1024 + 256 * j + 4 * lane));
;                 v[j] += a * *(const f32x4*)(sgate + 256 * j + 4 * lane); }
.LBB0_68:
	s_cmpk_lt_i32 s1, 0x4000
	s_cselect_b64 s[4:5], -1, 0
	s_or_b64 s[10:11], s[58:59], s[4:5]
	s_and_b64 vcc, exec, s[10:11]
	s_cbranch_vccnz .LBB0_70
	s_lshl_b64 s[4:5], s[92:93], 11
	v_lshl_add_u64 v[78:79], v[60:61], 0, s[4:5]
	v_add_co_u32_e32 v76, vcc, 0x400000, v78
	s_nop 0
	v_addc_co_u32_e32 v77, vcc, 0, v79, vcc
	global_load_dwordx2 v[110:111], v[78:79], off
	global_load_dwordx2 v[112:113], v[76:77], off
	global_load_dwordx2 v[114:115], v[78:79], off offset:512
	global_load_dwordx2 v[116:117], v[76:77], off offset:512
	global_load_dwordx2 v[118:119], v[78:79], off offset:1024
	global_load_dwordx2 v[120:121], v[76:77], off offset:1024
	global_load_dwordx2 v[122:123], v[78:79], off offset:1536
	global_load_dwordx2 v[124:125], v[76:77], off offset:1536
	global_load_dwordx4 v[126:129], v[52:53], off
	global_load_dwordx4 v[130:133], v[52:53], off offset:1024
	global_load_dwordx4 v[134:137], v[52:53], off offset:2048
	global_load_dwordx4 v[138:141], v[52:53], off offset:3072
	s_waitcnt vmcnt(0)
	v_lshlrev_b32_e32 v98, 16, v110
	v_and_b32_e32 v99, 0xffff0000, v110
	v_lshlrev_b32_e32 v100, 16, v111
	v_and_b32_e32 v101, 0xffff0000, v111
	v_pk_add_f32 v[98:99], v[98:99], 0 op_sel_hi:[1,0]
	v_pk_add_f32 v[100:101], v[100:101], 0 op_sel_hi:[1,0]
	v_lshlrev_b32_e32 v102, 16, v112
	v_and_b32_e32 v103, 0xffff0000, v112
	v_lshlrev_b32_e32 v104, 16, v113
	v_and_b32_e32 v105, 0xffff0000, v113
	v_pk_add_f32 v[98:99], v[98:99], v[102:103]
	v_pk_add_f32 v[100:101], v[100:101], v[104:105]
	v_pk_fma_f32 v[72:73], v[98:99], v[126:127], v[72:73]
	v_pk_fma_f32 v[74:75], v[100:101], v[128:129], v[74:75]
	v_lshlrev_b32_e32 v98, 16, v114
	v_and_b32_e32 v99, 0xffff0000, v114
	v_lshlrev_b32_e32 v100, 16, v115
	v_and_b32_e32 v101, 0xffff0000, v115
	v_pk_add_f32 v[98:99], v[98:99], 0 op_sel_hi:[1,0]
	v_pk_add_f32 v[100:101], v[100:101], 0 op_sel_hi:[1,0]
	v_lshlrev_b32_e32 v102, 16, v116
	v_and_b32_e32 v103, 0xffff0000, v116
	v_lshlrev_b32_e32 v104, 16, v117
	v_and_b32_e32 v105, 0xffff0000, v117
	v_pk_add_f32 v[98:99], v[98:99], v[102:103]
	v_pk_add_f32 v[100:101], v[100:101], v[104:105]
	v_pk_fma_f32 v[68:69], v[98:99], v[130:131], v[68:69]
	v_pk_fma_f32 v[70:71], v[100:101], v[132:133], v[70:71]
	v_lshlrev_b32_e32 v98, 16, v118
	v_and_b32_e32 v99, 0xffff0000, v118
	v_lshlrev_b32_e32 v100, 16, v119
	v_and_b32_e32 v101, 0xffff0000, v119
	v_pk_add_f32 v[98:99], v[98:99], 0 op_sel_hi:[1,0]
	v_pk_add_f32 v[100:101], v[100:101], 0 op_sel_hi:[1,0]
	v_lshlrev_b32_e32 v102, 16, v120
	v_and_b32_e32 v103, 0xffff0000, v120
	v_lshlrev_b32_e32 v104, 16, v121
	v_and_b32_e32 v105, 0xffff0000, v121
	v_pk_add_f32 v[98:99], v[98:99], v[102:103]
	v_pk_add_f32 v[100:101], v[100:101], v[104:105]
	v_pk_fma_f32 v[58:59], v[98:99], v[134:135], v[58:59]
	v_pk_fma_f32 v[62:63], v[100:101], v[136:137], v[62:63]
	v_lshlrev_b32_e32 v98, 16, v122
	v_and_b32_e32 v99, 0xffff0000, v122
	v_lshlrev_b32_e32 v100, 16, v123
	v_and_b32_e32 v101, 0xffff0000, v123
	v_pk_add_f32 v[98:99], v[98:99], 0 op_sel_hi:[1,0]
	v_pk_add_f32 v[100:101], v[100:101], 0 op_sel_hi:[1,0]
	v_lshlrev_b32_e32 v102, 16, v124
	v_and_b32_e32 v103, 0xffff0000, v124
	v_lshlrev_b32_e32 v104, 16, v125
	v_and_b32_e32 v105, 0xffff0000, v125
	v_pk_add_f32 v[98:99], v[98:99], v[102:103]
	v_pk_add_f32 v[100:101], v[100:101], v[104:105]
	v_pk_fma_f32 v[54:55], v[98:99], v[138:139], v[54:55]
	v_pk_fma_f32 v[56:57], v[100:101], v[140:141], v[56:57]
